# EpiSwiglu row-sum across quads via v_permlane16/32_swap instead of ds_bpermute round trips
# speedup vs baseline: 1.0050x; 1.0019x over previous
; __device__ __forceinline__ unsigned cvt_pk_bf16(float lo, float hi) { const f32x2 v = {lo, hi}; return __builtin_bit_cast(unsigned, __builtin_convertvector(v, bf16x2_t)); }
; __device__ __forceinline__ float fast_silu(float g) { return g * __builtin_amdgcn_rcpf(1.0f + __builtin_amdgcn_exp2f(-1.4426950408889634f * g)); }
; __device__ __forceinline__ float sum4(f32x4 v) { return (v.x + v.y) + (v.z + v.w); }
; __device__ __forceinline__ float quad_sum(float t, int lane) { t += shx(t, 16, lane); t += shx(t, 32, lane); return t; }
;     template <int A0, int A1> __device__ __forceinline__ void run(const f32x4 (&acc)[2][2][4][2], const Unit& u, int wr, int wc, int fr, int fq) const {
;         const int s = stream_of(u.pm);
;         const int cb = u.pn * 256 + wc * 32 + fq * 8;
;         const float* bp = sW + s * NFF + cb;
;         f32x4 bg[2], bu[2];
; #pragma unroll
;         for (int n = 0; n < 2; ++n) { bg[n] = *(const f32x4*)(bp + 4 * n); bu[n] = *(const f32x4*)(bp + 128 + 4 * n); }
;         const int row0 = u.pm * 256 + wr * 64 + fr;
; #pragma unroll
;         for (int ai = A0; ai < A1; ++ai)
; #pragma unroll
;             for (int m = 0; m < 4; ++m) {
;                 const int row = row0 + ai * 128 + m * 16;
;                 const float t = quad_sum(sum4(*(const f32x4*)(ssqp + (size_t)row * 16 + 4 * fq)), fq * 16 + fr);
;                 const float rr = rsqrtf(t * (1.0f / 1024.0f) + EPS);
;                 u32x4 w;
; #pragma unroll
;                 for (int n = 0; n < 2; ++n) {
;                     const f32x4 gg = acc[ai][0][m][n] * rr + bg[n], uu = acc[ai][1][m][n] * rr + bu[n];
;                     const float h0 = fast_silu(gg.x) * uu.x, h1 = fast_silu(gg.y) * uu.y, h2 = fast_silu(gg.z) * uu.z, h3 = fast_silu(gg.w) * uu.w;
;                     w[2 * n] = cvt_pk_bf16(h0, h1); w[2 * n + 1] = cvt_pk_bf16(h2, h3);
;                 }
;                 bf16_t* hp = H + (size_t)row * DFF + u.pn * 128 + wc * 32 + fq * 8;
;                 if (cnt) asm volatile("global_store_dwordx4 %0, %1, off sc0 sc1" :: "v"(hp), "v"(w) : "memory");
;                 else *(u32x4*)hp = w;
.LBB0_235:
	s_cmp_lt_u32 s16, 64
	s_cselect_b32 s7, s1, 0x2c00
	s_cmp_gt_i32 s16, 31
	s_cselect_b32 s7, s7, 0
	s_lshl_b32 s7, s7, 2
	v_lshl_add_u32 v160, s16, 8, v162
	v_lshl_or_b32 v32, s6, 8, v166
	s_add_u32 s20, s67, s7
	v_ashrrev_i32_e32 v161, 31, v160
	s_addc_u32 s21, s87, 0
	v_ashrrev_i32_e32 v33, 31, v32
	v_lshlrev_b64 v[168:169], 6, v[160:161]
	v_lshl_add_u64 v[40:41], v[32:33], 2, s[20:21]
	v_lshl_add_u64 v[168:169], v[154:155], 0, v[168:169]
	global_load_dwordx4 v[36:39], v[40:41], off offset:16
	global_load_dwordx4 v[44:47], v[40:41], off
	global_load_dwordx4 v[32:35], v[40:41], off offset:528
	s_nop 0
	global_load_dwordx4 v[40:43], v[40:41], off offset:512
	s_lshl_b32 s84, s6, 7
	global_load_dwordx4 v[224:227], v[168:169], off offset:1024
	global_load_dwordx4 v[228:231], v[168:169], off offset:2048
	global_load_dwordx4 v[232:235], v[168:169], off offset:3072
	v_mov_b32_e32 v236, 0x2000
	v_mov_b32_e32 v237, 0
	v_lshl_add_u64 v[236:237], v[168:169], 0, v[236:237]
	global_load_dwordx4 v[240:243], v[236:237], off
	global_load_dwordx4 v[244:247], v[236:237], off offset:1024
	global_load_dwordx4 v[248:251], v[236:237], off offset:2048
	global_load_dwordx4 v[168:171], v[168:169], off
	s_ashr_i32 s85, s84, 31
	s_waitcnt vmcnt(0)
	v_mov_b32_e32 v172, v169
	v_mov_b32_e32 v173, v170
	v_mov_b32_e32 v169, v171
	v_pk_add_f32 v[168:169], v[172:173], v[168:169]
	s_nop 0
	v_add_f32_e32 v161, v168, v169
	v_mov_b32_e32 v168, v161
	s_nop 1
	v_permlane16_swap_b32_e32 v161, v168
	v_add_f32_e32 v161, v161, v168
	v_mov_b32_e32 v168, v161
	s_nop 1
	v_permlane32_swap_b32_e32 v161, v168
	v_add_f32_e32 v161, v161, v168
	v_fmamk_f32 v161, v161, 0x3a800000, v252
	v_cmp_gt_f32_e32 vcc, s49, v161
	v_mul_f32_e32 v168, 0x4b800000, v161
	s_nop 0
	v_cndmask_b32_e32 v161, v161, v168, vcc
	v_rsq_f32_e32 v161, v161
	s_nop 0
	v_mul_f32_e32 v168, 0x45800000, v161
	v_cndmask_b32_e32 v168, v161, v168, vcc
	v_pk_fma_f32 v[142:143], v[142:143], v[168:169], v[44:45] op_sel_hi:[1,0,1]
	v_pk_fma_f32 v[144:145], v[144:145], v[168:169], v[46:47] op_sel_hi:[1,0,1]
	v_mul_f32_e32 v161, 0xbfb8aa3b, v142
	v_exp_f32_e32 v161, v161
	v_pk_fma_f32 v[134:135], v[134:135], v[168:169], v[40:41] op_sel_hi:[1,0,1]
	v_pk_fma_f32 v[136:137], v[136:137], v[168:169], v[42:43] op_sel_hi:[1,0,1]
	v_pk_fma_f32 v[138:139], v[138:139], v[168:169], v[36:37] op_sel_hi:[1,0,1]
	v_add_f32_e32 v161, 1.0, v161
	v_rcp_f32_e32 v170, v161
	v_mul_f32_e32 v161, 0xbfb8aa3b, v143
	v_exp_f32_e32 v161, v161
	v_pk_fma_f32 v[130:131], v[130:131], v[168:169], v[32:33] op_sel_hi:[1,0,1]
	v_pk_fma_f32 v[132:133], v[132:133], v[168:169], v[34:35] op_sel_hi:[1,0,1]
	s_andn2_b64 vcc, exec, s[24:25]
	v_add_f32_e32 v161, 1.0, v161
	v_rcp_f32_e32 v171, v161
	s_nop 0
	v_pk_mul_f32 v[142:143], v[142:143], v[170:171]
	s_nop 0
	v_pk_mul_f32 v[134:135], v[134:135], v[142:143]
	v_mul_f32_e32 v142, 0xbfb8aa3b, v144
	v_mul_f32_e32 v143, 0xbfb8aa3b, v145
	v_exp_f32_e32 v142, v142
	v_exp_f32_e32 v143, v143
	v_cvt_pk_bf16_f32 v134, v134, v135
	v_add_f32_e32 v142, 1.0, v142
	v_add_f32_e32 v143, 1.0, v143
	v_rcp_f32_e32 v142, v142
	v_rcp_f32_e32 v143, v143
	s_nop 0
	v_pk_mul_f32 v[142:143], v[144:145], v[142:143]
	s_nop 0
	v_pk_mul_f32 v[136:137], v[136:137], v[142:143]
	s_nop 0
	v_cvt_pk_bf16_f32 v135, v136, v137
	v_pk_fma_f32 v[136:137], v[140:141], v[168:169], v[38:39] op_sel_hi:[1,0,1]
	v_mul_f32_e32 v140, 0xbfb8aa3b, v138
	v_mul_f32_e32 v141, 0xbfb8aa3b, v139
	v_exp_f32_e32 v140, v140
	v_exp_f32_e32 v141, v141
	v_add_f32_e32 v140, 1.0, v140
	v_add_f32_e32 v141, 1.0, v141
	v_rcp_f32_e32 v140, v140
	v_rcp_f32_e32 v141, v141
	s_nop 0
	v_pk_mul_f32 v[138:139], v[138:139], v[140:141]
	s_nop 0
	v_pk_mul_f32 v[130:131], v[130:131], v[138:139]
	v_mul_f32_e32 v138, 0xbfb8aa3b, v136
	v_mul_f32_e32 v139, 0xbfb8aa3b, v137
	v_exp_f32_e32 v138, v138
	v_exp_f32_e32 v139, v139
	v_add_f32_e32 v138, 1.0, v138
	v_add_f32_e32 v139, 1.0, v139
	v_rcp_f32_e32 v138, v138
	v_rcp_f32_e32 v139, v139
	s_nop 0
	v_pk_mul_f32 v[136:137], v[136:137], v[138:139]
	s_nop 0
	v_pk_mul_f32 v[132:133], v[132:133], v[136:137]
	v_cvt_pk_bf16_f32 v136, v130, v131
	v_mov_b64_e32 v[130:131], s[12:13]
	v_mad_i64_i32 v[130:131], s[20:21], v160, s1, v[130:131]
	v_lshl_add_u64 v[130:131], s[84:85], 1, v[130:131]
	v_cvt_pk_bf16_f32 v137, v132, v133
	v_lshl_add_u64 v[130:131], v[130:131], 0, s[52:53]
	v_cndmask_b32_e64 v132, 0, 1, s[24:25]
	v_lshl_add_u64 v[130:131], v[130:131], 0, v[128:129]
	v_cmp_ne_u32_e64 s[6:7], 1, v132
	s_cbranch_vccnz .LBB0_267
	global_store_dwordx4 v[130:131], v[134:137], off sc0 sc1
	s_cbranch_execnz .LBB0_238

; __device__ __forceinline__ unsigned cvt_pk_bf16(float lo, float hi) { const f32x2 v = {lo, hi}; return __builtin_bit_cast(unsigned, __builtin_convertvector(v, bf16x2_t)); }
; __device__ __forceinline__ float fast_silu(float g) { return g * __builtin_amdgcn_rcpf(1.0f + __builtin_amdgcn_exp2f(-1.4426950408889634f * g)); }
; __device__ __forceinline__ float sum4(f32x4 v) { return (v.x + v.y) + (v.z + v.w); }
; __device__ __forceinline__ float quad_sum(float t, int lane) { t += shx(t, 16, lane); t += shx(t, 32, lane); return t; }
;     template <int A0, int A1> __device__ __forceinline__ void run(const f32x4 (&acc)[2][2][4][2], const Unit& u, int wr, int wc, int fr, int fq) const {
;     ...
;             for (int m = 0; m < 4; ++m) {
;                 const int row = row0 + ai * 128 + m * 16;
;                 const float t = quad_sum(sum4(*(const f32x4*)(ssqp + (size_t)row * 16 + 4 * fq)), fq * 16 + fr);
;                 const float rr = rsqrtf(t * (1.0f / 1024.0f) + EPS);
;                 u32x4 w;
; #pragma unroll
;                 for (int n = 0; n < 2; ++n) {
;                     const f32x4 gg = acc[ai][0][m][n] * rr + bg[n], uu = acc[ai][1][m][n] * rr + bu[n];
;                     const float h0 = fast_silu(gg.x) * uu.x, h1 = fast_silu(gg.y) * uu.y, h2 = fast_silu(gg.z) * uu.z, h3 = fast_silu(gg.w) * uu.w;
;                     w[2 * n] = cvt_pk_bf16(h0, h1); w[2 * n + 1] = cvt_pk_bf16(h2, h3);
;                 }
;                 bf16_t* hp = H + (size_t)row * DFF + u.pn * 128 + wc * 32 + fq * 8;
;                 if (cnt) asm volatile("global_store_dwordx4 %0, %1, off sc0 sc1" :: "v"(hp), "v"(w) : "memory");
;                 else *(u32x4*)hp = w;
.LBB0_238:
	v_or_b32_e32 v130, 16, v160
	v_ashrrev_i32_e32 v131, 31, v130
	v_mov_b64_e32 v[132:133], v[224:225]
	v_mov_b64_e32 v[134:135], v[226:227]
	global_load_dwordx4 v[224:227], v[236:237], off offset:3072
	v_mov_b32_e32 v136, v133
	v_mov_b32_e32 v137, v134
	v_mov_b32_e32 v133, v135
	v_pk_add_f32 v[132:133], v[136:137], v[132:133]
	s_nop 0
	v_add_f32_e32 v131, v132, v133
	v_mov_b32_e32 v132, v131
	s_nop 1
	v_permlane16_swap_b32_e32 v131, v132
	v_add_f32_e32 v131, v131, v132
	v_mov_b32_e32 v132, v131
	s_nop 1
	v_permlane32_swap_b32_e32 v131, v132
	v_add_f32_e32 v131, v131, v132
	v_fmamk_f32 v131, v131, 0x3a800000, v252
	v_cmp_gt_f32_e32 vcc, s49, v131
	v_mul_f32_e32 v132, 0x4b800000, v131
	s_nop 0
	v_cndmask_b32_e32 v131, v131, v132, vcc
	v_rsq_f32_e32 v131, v131
	s_nop 0
	v_mul_f32_e32 v132, 0x45800000, v131
	v_cndmask_b32_e32 v132, v131, v132, vcc
	v_pk_fma_f32 v[124:125], v[124:125], v[132:133], v[44:45] op_sel_hi:[1,0,1]
	v_pk_fma_f32 v[126:127], v[126:127], v[132:133], v[46:47] op_sel_hi:[1,0,1]
	v_mul_f32_e32 v131, 0xbfb8aa3b, v124
	v_exp_f32_e32 v131, v131
	v_pk_fma_f32 v[116:117], v[116:117], v[132:133], v[40:41] op_sel_hi:[1,0,1]
	v_pk_fma_f32 v[118:119], v[118:119], v[132:133], v[42:43] op_sel_hi:[1,0,1]
	v_pk_fma_f32 v[120:121], v[120:121], v[132:133], v[36:37] op_sel_hi:[1,0,1]
	v_add_f32_e32 v131, 1.0, v131
	v_rcp_f32_e32 v134, v131
	v_mul_f32_e32 v131, 0xbfb8aa3b, v125
	v_exp_f32_e32 v131, v131
	v_pk_fma_f32 v[112:113], v[112:113], v[132:133], v[32:33] op_sel_hi:[1,0,1]
	v_pk_fma_f32 v[114:115], v[114:115], v[132:133], v[34:35] op_sel_hi:[1,0,1]
	s_and_b64 vcc, exec, s[6:7]
	v_add_f32_e32 v131, 1.0, v131
	v_rcp_f32_e32 v135, v131
	s_nop 0
	v_pk_mul_f32 v[124:125], v[124:125], v[134:135]
	s_nop 0
	v_pk_mul_f32 v[116:117], v[116:117], v[124:125]
	v_mul_f32_e32 v124, 0xbfb8aa3b, v126
	v_mul_f32_e32 v125, 0xbfb8aa3b, v127
	v_exp_f32_e32 v124, v124
	v_exp_f32_e32 v125, v125
	v_cvt_pk_bf16_f32 v116, v116, v117
	v_add_f32_e32 v124, 1.0, v124
	v_add_f32_e32 v125, 1.0, v125
	v_rcp_f32_e32 v124, v124
	v_rcp_f32_e32 v125, v125
	s_nop 0
	v_pk_mul_f32 v[124:125], v[126:127], v[124:125]
	s_nop 0
	v_pk_mul_f32 v[118:119], v[118:119], v[124:125]
	s_nop 0
	v_cvt_pk_bf16_f32 v117, v118, v119
	v_pk_fma_f32 v[118:119], v[122:123], v[132:133], v[38:39] op_sel_hi:[1,0,1]
	v_mul_f32_e32 v122, 0xbfb8aa3b, v120
	v_mul_f32_e32 v123, 0xbfb8aa3b, v121
	v_exp_f32_e32 v122, v122
	v_exp_f32_e32 v123, v123
	v_add_f32_e32 v122, 1.0, v122
	v_add_f32_e32 v123, 1.0, v123
	v_rcp_f32_e32 v122, v122
	v_rcp_f32_e32 v123, v123
	s_nop 0
	v_pk_mul_f32 v[120:121], v[120:121], v[122:123]
	s_nop 0
	v_pk_mul_f32 v[112:113], v[112:113], v[120:121]
	v_mul_f32_e32 v120, 0xbfb8aa3b, v118
	v_mul_f32_e32 v121, 0xbfb8aa3b, v119
	v_exp_f32_e32 v120, v120
	v_exp_f32_e32 v121, v121
	v_add_f32_e32 v120, 1.0, v120
	v_add_f32_e32 v121, 1.0, v121
	v_rcp_f32_e32 v120, v120
	v_rcp_f32_e32 v121, v121
	s_nop 0
	v_pk_mul_f32 v[118:119], v[118:119], v[120:121]
	s_nop 0
	v_pk_mul_f32 v[114:115], v[114:115], v[118:119]
	v_cvt_pk_bf16_f32 v118, v112, v113
	v_mov_b64_e32 v[112:113], s[12:13]
	v_mad_i64_i32 v[112:113], s[20:21], v130, s1, v[112:113]
	v_lshl_add_u64 v[112:113], s[84:85], 1, v[112:113]
	v_lshl_add_u64 v[112:113], v[112:113], 0, s[52:53]
	v_cvt_pk_bf16_f32 v119, v114, v115
	v_lshl_add_u64 v[112:113], v[112:113], 0, v[128:129]
	s_cbranch_vccnz .LBB0_268
	global_store_dwordx4 v[112:113], v[116:119], off sc0 sc1
	s_cbranch_execnz .LBB0_241

; __device__ __forceinline__ unsigned cvt_pk_bf16(float lo, float hi) { const f32x2 v = {lo, hi}; return __builtin_bit_cast(unsigned, __builtin_convertvector(v, bf16x2_t)); }
; __device__ __forceinline__ float fast_silu(float g) { return g * __builtin_amdgcn_rcpf(1.0f + __builtin_amdgcn_exp2f(-1.4426950408889634f * g)); }
; __device__ __forceinline__ float sum4(f32x4 v) { return (v.x + v.y) + (v.z + v.w); }
; __device__ __forceinline__ float quad_sum(float t, int lane) { t += shx(t, 16, lane); t += shx(t, 32, lane); return t; }
;     template <int A0, int A1> __device__ __forceinline__ void run(const f32x4 (&acc)[2][2][4][2], const Unit& u, int wr, int wc, int fr, int fq) const {
;     ...
;             for (int m = 0; m < 4; ++m) {
;                 const int row = row0 + ai * 128 + m * 16;
;                 const float t = quad_sum(sum4(*(const f32x4*)(ssqp + (size_t)row * 16 + 4 * fq)), fq * 16 + fr);
;                 const float rr = rsqrtf(t * (1.0f / 1024.0f) + EPS);
;                 u32x4 w;
; #pragma unroll
;                 for (int n = 0; n < 2; ++n) {
;                     const f32x4 gg = acc[ai][0][m][n] * rr + bg[n], uu = acc[ai][1][m][n] * rr + bu[n];
;                     const float h0 = fast_silu(gg.x) * uu.x, h1 = fast_silu(gg.y) * uu.y, h2 = fast_silu(gg.z) * uu.z, h3 = fast_silu(gg.w) * uu.w;
;                     w[2 * n] = cvt_pk_bf16(h0, h1); w[2 * n + 1] = cvt_pk_bf16(h2, h3);
;                 }
;                 bf16_t* hp = H + (size_t)row * DFF + u.pn * 128 + wc * 32 + fq * 8;
;                 if (cnt) asm volatile("global_store_dwordx4 %0, %1, off sc0 sc1" :: "v"(hp), "v"(w) : "memory");
;                 else *(u32x4*)hp = w;
.LBB0_241:
	v_or_b32_e32 v112, 32, v160
	v_ashrrev_i32_e32 v113, 31, v112
	v_mov_b64_e32 v[114:115], v[228:229]
	v_mov_b64_e32 v[116:117], v[230:231]
	v_mov_b32_e32 v118, v115
	v_mov_b32_e32 v119, v116
	v_mov_b32_e32 v115, v117
	v_pk_add_f32 v[114:115], v[118:119], v[114:115]
	s_nop 0
	v_add_f32_e32 v113, v114, v115
	v_mov_b32_e32 v114, v113
	s_nop 1
	v_permlane16_swap_b32_e32 v113, v114
	v_add_f32_e32 v113, v113, v114
	v_mov_b32_e32 v114, v113
	s_nop 1
	v_permlane32_swap_b32_e32 v113, v114
	v_add_f32_e32 v113, v113, v114
	v_fmamk_f32 v113, v113, 0x3a800000, v252
	v_cmp_gt_f32_e32 vcc, s49, v113
	v_mul_f32_e32 v114, 0x4b800000, v113
	s_nop 0
	v_cndmask_b32_e32 v113, v113, v114, vcc
	v_rsq_f32_e32 v113, v113
	s_nop 0
	v_mul_f32_e32 v114, 0x45800000, v113
	v_cndmask_b32_e32 v114, v113, v114, vcc
	v_pk_fma_f32 v[108:109], v[108:109], v[114:115], v[44:45] op_sel_hi:[1,0,1]
	v_pk_fma_f32 v[110:111], v[110:111], v[114:115], v[46:47] op_sel_hi:[1,0,1]
	v_mul_f32_e32 v113, 0xbfb8aa3b, v108
	v_exp_f32_e32 v113, v113
	v_pk_fma_f32 v[100:101], v[100:101], v[114:115], v[40:41] op_sel_hi:[1,0,1]
	v_pk_fma_f32 v[102:103], v[102:103], v[114:115], v[42:43] op_sel_hi:[1,0,1]
	v_pk_fma_f32 v[104:105], v[104:105], v[114:115], v[36:37] op_sel_hi:[1,0,1]
	v_add_f32_e32 v113, 1.0, v113
	v_rcp_f32_e32 v116, v113
	v_mul_f32_e32 v113, 0xbfb8aa3b, v109
	v_exp_f32_e32 v113, v113
	v_pk_fma_f32 v[96:97], v[96:97], v[114:115], v[32:33] op_sel_hi:[1,0,1]
	v_pk_fma_f32 v[98:99], v[98:99], v[114:115], v[34:35] op_sel_hi:[1,0,1]
	s_and_b64 vcc, exec, s[6:7]
	v_add_f32_e32 v113, 1.0, v113
	v_rcp_f32_e32 v117, v113
	s_nop 0
	v_pk_mul_f32 v[108:109], v[108:109], v[116:117]
	s_nop 0
	v_pk_mul_f32 v[100:101], v[100:101], v[108:109]
	v_mul_f32_e32 v108, 0xbfb8aa3b, v110
	v_mul_f32_e32 v109, 0xbfb8aa3b, v111
	v_exp_f32_e32 v108, v108
	v_exp_f32_e32 v109, v109
	v_cvt_pk_bf16_f32 v100, v100, v101
	v_add_f32_e32 v108, 1.0, v108
	v_add_f32_e32 v109, 1.0, v109
	v_rcp_f32_e32 v108, v108
	v_rcp_f32_e32 v109, v109
	s_nop 0
	v_pk_mul_f32 v[108:109], v[110:111], v[108:109]
	s_nop 0
	v_pk_mul_f32 v[102:103], v[102:103], v[108:109]
	s_nop 0
	v_cvt_pk_bf16_f32 v101, v102, v103
	v_pk_fma_f32 v[102:103], v[106:107], v[114:115], v[38:39] op_sel_hi:[1,0,1]
	v_mul_f32_e32 v106, 0xbfb8aa3b, v104
	v_mul_f32_e32 v107, 0xbfb8aa3b, v105
	v_exp_f32_e32 v106, v106
	v_exp_f32_e32 v107, v107
	v_add_f32_e32 v106, 1.0, v106
	v_add_f32_e32 v107, 1.0, v107
	v_rcp_f32_e32 v106, v106
	v_rcp_f32_e32 v107, v107
	s_nop 0
	v_pk_mul_f32 v[104:105], v[104:105], v[106:107]
	s_nop 0
	v_pk_mul_f32 v[96:97], v[96:97], v[104:105]
	v_mul_f32_e32 v104, 0xbfb8aa3b, v102
	v_mul_f32_e32 v105, 0xbfb8aa3b, v103
	v_exp_f32_e32 v104, v104
	v_exp_f32_e32 v105, v105
	v_add_f32_e32 v104, 1.0, v104
	v_add_f32_e32 v105, 1.0, v105
	v_rcp_f32_e32 v104, v104
	v_rcp_f32_e32 v105, v105
	s_nop 0
	v_pk_mul_f32 v[102:103], v[102:103], v[104:105]
	s_nop 0
	v_pk_mul_f32 v[98:99], v[98:99], v[102:103]
	v_cvt_pk_bf16_f32 v102, v96, v97
	v_mov_b64_e32 v[96:97], s[12:13]
	v_mad_i64_i32 v[96:97], s[20:21], v112, s1, v[96:97]
	v_lshl_add_u64 v[96:97], s[84:85], 1, v[96:97]
	v_lshl_add_u64 v[96:97], v[96:97], 0, s[52:53]
	v_cvt_pk_bf16_f32 v103, v98, v99
	v_lshl_add_u64 v[96:97], v[96:97], 0, v[128:129]
	s_cbranch_vccnz .LBB0_269
	global_store_dwordx4 v[96:97], v[100:103], off sc0 sc1
	s_cbranch_execnz .LBB0_244

; __device__ __forceinline__ unsigned cvt_pk_bf16(float lo, float hi) { const f32x2 v = {lo, hi}; return __builtin_bit_cast(unsigned, __builtin_convertvector(v, bf16x2_t)); }
; __device__ __forceinline__ float fast_silu(float g) { return g * __builtin_amdgcn_rcpf(1.0f + __builtin_amdgcn_exp2f(-1.4426950408889634f * g)); }
; __device__ __forceinline__ float sum4(f32x4 v) { return (v.x + v.y) + (v.z + v.w); }
; __device__ __forceinline__ float quad_sum(float t, int lane) { t += shx(t, 16, lane); t += shx(t, 32, lane); return t; }
;     template <int A0, int A1> __device__ __forceinline__ void run(const f32x4 (&acc)[2][2][4][2], const Unit& u, int wr, int wc, int fr, int fq) const {
;     ...
;             for (int m = 0; m < 4; ++m) {
;                 const int row = row0 + ai * 128 + m * 16;
;                 const float t = quad_sum(sum4(*(const f32x4*)(ssqp + (size_t)row * 16 + 4 * fq)), fq * 16 + fr);
;                 const float rr = rsqrtf(t * (1.0f / 1024.0f) + EPS);
;                 u32x4 w;
; #pragma unroll
;                 for (int n = 0; n < 2; ++n) {
;                     const f32x4 gg = acc[ai][0][m][n] * rr + bg[n], uu = acc[ai][1][m][n] * rr + bu[n];
;                     const float h0 = fast_silu(gg.x) * uu.x, h1 = fast_silu(gg.y) * uu.y, h2 = fast_silu(gg.z) * uu.z, h3 = fast_silu(gg.w) * uu.w;
;                     w[2 * n] = cvt_pk_bf16(h0, h1); w[2 * n + 1] = cvt_pk_bf16(h2, h3);
;                 }
;                 bf16_t* hp = H + (size_t)row * DFF + u.pn * 128 + wc * 32 + fq * 8;
;                 if (cnt) asm volatile("global_store_dwordx4 %0, %1, off sc0 sc1" :: "v"(hp), "v"(w) : "memory");
;                 else *(u32x4*)hp = w;
.LBB0_244:
	v_or_b32_e32 v96, 48, v160
	v_ashrrev_i32_e32 v97, 31, v96
	v_mov_b64_e32 v[98:99], v[232:233]
	v_mov_b64_e32 v[100:101], v[234:235]
	v_mov_b32_e32 v102, v99
	v_mov_b32_e32 v103, v100
	v_mov_b32_e32 v99, v101
	v_pk_add_f32 v[98:99], v[102:103], v[98:99]
	s_nop 0
	v_add_f32_e32 v97, v98, v99
	v_mov_b32_e32 v98, v97
	s_nop 1
	v_permlane16_swap_b32_e32 v97, v98
	v_add_f32_e32 v97, v97, v98
	v_mov_b32_e32 v98, v97
	s_nop 1
	v_permlane32_swap_b32_e32 v97, v98
	v_add_f32_e32 v97, v97, v98
	v_fmamk_f32 v97, v97, 0x3a800000, v252
	v_cmp_gt_f32_e32 vcc, s49, v97
	v_mul_f32_e32 v98, 0x4b800000, v97
	s_nop 0
	v_cndmask_b32_e32 v97, v97, v98, vcc
	v_rsq_f32_e32 v97, v97
	s_nop 0
	v_mul_f32_e32 v98, 0x45800000, v97
	v_cndmask_b32_e32 v98, v97, v98, vcc
	v_pk_fma_f32 v[92:93], v[92:93], v[98:99], v[44:45] op_sel_hi:[1,0,1]
	v_pk_fma_f32 v[94:95], v[94:95], v[98:99], v[46:47] op_sel_hi:[1,0,1]
	v_mul_f32_e32 v97, 0xbfb8aa3b, v92
	v_exp_f32_e32 v97, v97
	v_pk_fma_f32 v[84:85], v[84:85], v[98:99], v[40:41] op_sel_hi:[1,0,1]
	v_pk_fma_f32 v[86:87], v[86:87], v[98:99], v[42:43] op_sel_hi:[1,0,1]
	v_pk_fma_f32 v[88:89], v[88:89], v[98:99], v[36:37] op_sel_hi:[1,0,1]
	v_add_f32_e32 v97, 1.0, v97
	v_rcp_f32_e32 v100, v97
	v_mul_f32_e32 v97, 0xbfb8aa3b, v93
	v_exp_f32_e32 v97, v97
	v_pk_fma_f32 v[80:81], v[80:81], v[98:99], v[32:33] op_sel_hi:[1,0,1]
	v_pk_fma_f32 v[82:83], v[82:83], v[98:99], v[34:35] op_sel_hi:[1,0,1]
	s_and_b64 vcc, exec, s[6:7]
	v_add_f32_e32 v97, 1.0, v97
	v_rcp_f32_e32 v101, v97
	s_nop 0
	v_pk_mul_f32 v[92:93], v[92:93], v[100:101]
	s_nop 0
	v_pk_mul_f32 v[84:85], v[84:85], v[92:93]
	v_mul_f32_e32 v92, 0xbfb8aa3b, v94
	v_mul_f32_e32 v93, 0xbfb8aa3b, v95
	v_exp_f32_e32 v92, v92
	v_exp_f32_e32 v93, v93
	v_cvt_pk_bf16_f32 v84, v84, v85
	v_add_f32_e32 v92, 1.0, v92
	v_add_f32_e32 v93, 1.0, v93
	v_rcp_f32_e32 v92, v92
	v_rcp_f32_e32 v93, v93
	s_nop 0
	v_pk_mul_f32 v[92:93], v[94:95], v[92:93]
	s_nop 0
	v_pk_mul_f32 v[86:87], v[86:87], v[92:93]
	s_nop 0
	v_cvt_pk_bf16_f32 v85, v86, v87
	v_pk_fma_f32 v[86:87], v[90:91], v[98:99], v[38:39] op_sel_hi:[1,0,1]
	v_mul_f32_e32 v90, 0xbfb8aa3b, v88
	v_mul_f32_e32 v91, 0xbfb8aa3b, v89
	v_exp_f32_e32 v90, v90
	v_exp_f32_e32 v91, v91
	v_add_f32_e32 v90, 1.0, v90
	v_add_f32_e32 v91, 1.0, v91
	v_rcp_f32_e32 v90, v90
	v_rcp_f32_e32 v91, v91
	s_nop 0
	v_pk_mul_f32 v[88:89], v[88:89], v[90:91]
	s_nop 0
	v_pk_mul_f32 v[80:81], v[80:81], v[88:89]
	v_mul_f32_e32 v88, 0xbfb8aa3b, v86
	v_mul_f32_e32 v89, 0xbfb8aa3b, v87
	v_exp_f32_e32 v88, v88
	v_exp_f32_e32 v89, v89
	v_add_f32_e32 v88, 1.0, v88
	v_add_f32_e32 v89, 1.0, v89
	v_rcp_f32_e32 v88, v88
	v_rcp_f32_e32 v89, v89
	s_nop 0
	v_pk_mul_f32 v[86:87], v[86:87], v[88:89]
	s_nop 0
	v_pk_mul_f32 v[82:83], v[82:83], v[86:87]
	v_cvt_pk_bf16_f32 v86, v80, v81
	v_mov_b64_e32 v[80:81], s[12:13]
	v_mad_i64_i32 v[80:81], s[20:21], v96, s1, v[80:81]
	v_lshl_add_u64 v[80:81], s[84:85], 1, v[80:81]
	v_lshl_add_u64 v[80:81], v[80:81], 0, s[52:53]
	v_cvt_pk_bf16_f32 v87, v82, v83
	v_lshl_add_u64 v[80:81], v[80:81], 0, v[128:129]
	s_cbranch_vccnz .LBB0_270
	global_store_dwordx4 v[80:81], v[84:87], off sc0 sc1
	s_cbranch_execnz .LBB0_247

; __device__ __forceinline__ unsigned cvt_pk_bf16(float lo, float hi) { const f32x2 v = {lo, hi}; return __builtin_bit_cast(unsigned, __builtin_convertvector(v, bf16x2_t)); }
; __device__ __forceinline__ float fast_silu(float g) { return g * __builtin_amdgcn_rcpf(1.0f + __builtin_amdgcn_exp2f(-1.4426950408889634f * g)); }
; __device__ __forceinline__ float sum4(f32x4 v) { return (v.x + v.y) + (v.z + v.w); }
; __device__ __forceinline__ float quad_sum(float t, int lane) { t += shx(t, 16, lane); t += shx(t, 32, lane); return t; }
;     template <int A0, int A1> __device__ __forceinline__ void run(const f32x4 (&acc)[2][2][4][2], const Unit& u, int wr, int wc, int fr, int fq) const {
;     ...
;             for (int m = 0; m < 4; ++m) {
;                 const int row = row0 + ai * 128 + m * 16;
;                 const float t = quad_sum(sum4(*(const f32x4*)(ssqp + (size_t)row * 16 + 4 * fq)), fq * 16 + fr);
;                 const float rr = rsqrtf(t * (1.0f / 1024.0f) + EPS);
;                 u32x4 w;
; #pragma unroll
;                 for (int n = 0; n < 2; ++n) {
;                     const f32x4 gg = acc[ai][0][m][n] * rr + bg[n], uu = acc[ai][1][m][n] * rr + bu[n];
;                     const float h0 = fast_silu(gg.x) * uu.x, h1 = fast_silu(gg.y) * uu.y, h2 = fast_silu(gg.z) * uu.z, h3 = fast_silu(gg.w) * uu.w;
;                     w[2 * n] = cvt_pk_bf16(h0, h1); w[2 * n + 1] = cvt_pk_bf16(h2, h3);
;                 }
;                 bf16_t* hp = H + (size_t)row * DFF + u.pn * 128 + wc * 32 + fq * 8;
;                 if (cnt) asm volatile("global_store_dwordx4 %0, %1, off sc0 sc1" :: "v"(hp), "v"(w) : "memory");
;                 else *(u32x4*)hp = w;
.LBB0_247:
	v_add_u32_e32 v80, 0x80, v160
	v_ashrrev_i32_e32 v81, 31, v80
	v_mov_b64_e32 v[82:83], v[240:241]
	v_mov_b64_e32 v[84:85], v[242:243]
	v_mov_b32_e32 v86, v83
	v_mov_b32_e32 v87, v84
	v_mov_b32_e32 v83, v85
	v_pk_add_f32 v[82:83], v[86:87], v[82:83]
	s_nop 0
	v_add_f32_e32 v81, v82, v83
	v_mov_b32_e32 v82, v81
	s_nop 1
	v_permlane16_swap_b32_e32 v81, v82
	v_add_f32_e32 v81, v81, v82
	v_mov_b32_e32 v82, v81
	s_nop 1
	v_permlane32_swap_b32_e32 v81, v82
	v_add_f32_e32 v81, v81, v82
	v_fmamk_f32 v81, v81, 0x3a800000, v252
	v_cmp_gt_f32_e32 vcc, s49, v81
	v_mul_f32_e32 v82, 0x4b800000, v81
	s_nop 0
	v_cndmask_b32_e32 v81, v81, v82, vcc
	v_rsq_f32_e32 v81, v81
	s_nop 0
	v_mul_f32_e32 v82, 0x45800000, v81
	v_cndmask_b32_e32 v82, v81, v82, vcc
	v_pk_fma_f32 v[76:77], v[76:77], v[82:83], v[44:45] op_sel_hi:[1,0,1]
	v_pk_fma_f32 v[78:79], v[78:79], v[82:83], v[46:47] op_sel_hi:[1,0,1]
	v_mul_f32_e32 v81, 0xbfb8aa3b, v76
	v_exp_f32_e32 v81, v81
	v_pk_fma_f32 v[68:69], v[68:69], v[82:83], v[40:41] op_sel_hi:[1,0,1]
	v_pk_fma_f32 v[70:71], v[70:71], v[82:83], v[42:43] op_sel_hi:[1,0,1]
	v_pk_fma_f32 v[72:73], v[72:73], v[82:83], v[36:37] op_sel_hi:[1,0,1]
	v_add_f32_e32 v81, 1.0, v81
	v_rcp_f32_e32 v84, v81
	v_mul_f32_e32 v81, 0xbfb8aa3b, v77
	v_exp_f32_e32 v81, v81
	v_pk_fma_f32 v[64:65], v[64:65], v[82:83], v[32:33] op_sel_hi:[1,0,1]
	v_pk_fma_f32 v[66:67], v[66:67], v[82:83], v[34:35] op_sel_hi:[1,0,1]
	s_and_b64 vcc, exec, s[6:7]
	v_add_f32_e32 v81, 1.0, v81
	v_rcp_f32_e32 v85, v81
	s_nop 0
	v_pk_mul_f32 v[76:77], v[76:77], v[84:85]
	s_nop 0
	v_pk_mul_f32 v[68:69], v[68:69], v[76:77]
	v_mul_f32_e32 v76, 0xbfb8aa3b, v78
	v_mul_f32_e32 v77, 0xbfb8aa3b, v79
	v_exp_f32_e32 v76, v76
	v_exp_f32_e32 v77, v77
	v_cvt_pk_bf16_f32 v68, v68, v69
	v_add_f32_e32 v76, 1.0, v76
	v_add_f32_e32 v77, 1.0, v77
	v_rcp_f32_e32 v76, v76
	v_rcp_f32_e32 v77, v77
	s_nop 0
	v_pk_mul_f32 v[76:77], v[78:79], v[76:77]
	s_nop 0
	v_pk_mul_f32 v[70:71], v[70:71], v[76:77]
	s_nop 0
	v_cvt_pk_bf16_f32 v69, v70, v71
	v_pk_fma_f32 v[70:71], v[74:75], v[82:83], v[38:39] op_sel_hi:[1,0,1]
	v_mul_f32_e32 v74, 0xbfb8aa3b, v72
	v_mul_f32_e32 v75, 0xbfb8aa3b, v73
	v_exp_f32_e32 v74, v74
	v_exp_f32_e32 v75, v75
	v_add_f32_e32 v74, 1.0, v74
	v_add_f32_e32 v75, 1.0, v75
	v_rcp_f32_e32 v74, v74
	v_rcp_f32_e32 v75, v75
	s_nop 0
	v_pk_mul_f32 v[72:73], v[72:73], v[74:75]
	s_nop 0
	v_pk_mul_f32 v[64:65], v[64:65], v[72:73]
	v_mul_f32_e32 v72, 0xbfb8aa3b, v70
	v_mul_f32_e32 v73, 0xbfb8aa3b, v71
	v_exp_f32_e32 v72, v72
	v_exp_f32_e32 v73, v73
	v_add_f32_e32 v72, 1.0, v72
	v_add_f32_e32 v73, 1.0, v73
	v_rcp_f32_e32 v72, v72
	v_rcp_f32_e32 v73, v73
	s_nop 0
	v_pk_mul_f32 v[70:71], v[70:71], v[72:73]
	s_nop 0
	v_pk_mul_f32 v[66:67], v[66:67], v[70:71]
	v_cvt_pk_bf16_f32 v70, v64, v65
	v_mov_b64_e32 v[64:65], s[12:13]
	v_mad_i64_i32 v[64:65], s[20:21], v80, s1, v[64:65]
	v_lshl_add_u64 v[64:65], s[84:85], 1, v[64:65]
	v_lshl_add_u64 v[64:65], v[64:65], 0, s[52:53]
	v_cvt_pk_bf16_f32 v71, v66, v67
	v_lshl_add_u64 v[64:65], v[64:65], 0, v[128:129]
	s_cbranch_vccnz .LBB0_271
	global_store_dwordx4 v[64:65], v[68:71], off sc0 sc1
	s_cbranch_execnz .LBB0_250

; __device__ __forceinline__ unsigned cvt_pk_bf16(float lo, float hi) { const f32x2 v = {lo, hi}; return __builtin_bit_cast(unsigned, __builtin_convertvector(v, bf16x2_t)); }
; __device__ __forceinline__ float fast_silu(float g) { return g * __builtin_amdgcn_rcpf(1.0f + __builtin_amdgcn_exp2f(-1.4426950408889634f * g)); }
; __device__ __forceinline__ float sum4(f32x4 v) { return (v.x + v.y) + (v.z + v.w); }
; __device__ __forceinline__ float quad_sum(float t, int lane) { t += shx(t, 16, lane); t += shx(t, 32, lane); return t; }
;     template <int A0, int A1> __device__ __forceinline__ void run(const f32x4 (&acc)[2][2][4][2], const Unit& u, int wr, int wc, int fr, int fq) const {
;     ...
;             for (int m = 0; m < 4; ++m) {
;                 const int row = row0 + ai * 128 + m * 16;
;                 const float t = quad_sum(sum4(*(const f32x4*)(ssqp + (size_t)row * 16 + 4 * fq)), fq * 16 + fr);
;                 const float rr = rsqrtf(t * (1.0f / 1024.0f) + EPS);
;                 u32x4 w;
; #pragma unroll
;                 for (int n = 0; n < 2; ++n) {
;                     const f32x4 gg = acc[ai][0][m][n] * rr + bg[n], uu = acc[ai][1][m][n] * rr + bu[n];
;                     const float h0 = fast_silu(gg.x) * uu.x, h1 = fast_silu(gg.y) * uu.y, h2 = fast_silu(gg.z) * uu.z, h3 = fast_silu(gg.w) * uu.w;
;                     w[2 * n] = cvt_pk_bf16(h0, h1); w[2 * n + 1] = cvt_pk_bf16(h2, h3);
;                 }
;                 bf16_t* hp = H + (size_t)row * DFF + u.pn * 128 + wc * 32 + fq * 8;
;                 if (cnt) asm volatile("global_store_dwordx4 %0, %1, off sc0 sc1" :: "v"(hp), "v"(w) : "memory");
;                 else *(u32x4*)hp = w;
.LBB0_250:
	v_add_u32_e32 v64, 0x90, v160
	v_ashrrev_i32_e32 v65, 31, v64
	v_mov_b64_e32 v[66:67], v[244:245]
	v_mov_b64_e32 v[68:69], v[246:247]
	v_mov_b32_e32 v70, v67
	v_mov_b32_e32 v71, v68
	v_mov_b32_e32 v67, v69
	v_pk_add_f32 v[66:67], v[70:71], v[66:67]
	s_nop 0
	v_add_f32_e32 v65, v66, v67
	v_mov_b32_e32 v66, v65
	s_nop 1
	v_permlane16_swap_b32_e32 v65, v66
	v_add_f32_e32 v65, v65, v66
	v_mov_b32_e32 v66, v65
	s_nop 1
	v_permlane32_swap_b32_e32 v65, v66
	v_add_f32_e32 v65, v65, v66
	v_fmamk_f32 v65, v65, 0x3a800000, v252
	v_cmp_gt_f32_e32 vcc, s49, v65
	v_mul_f32_e32 v66, 0x4b800000, v65
	s_nop 0
	v_cndmask_b32_e32 v65, v65, v66, vcc
	v_rsq_f32_e32 v65, v65
	s_nop 0
	v_mul_f32_e32 v66, 0x45800000, v65
	v_cndmask_b32_e32 v66, v65, v66, vcc
	v_pk_fma_f32 v[60:61], v[60:61], v[66:67], v[44:45] op_sel_hi:[1,0,1]
	v_pk_fma_f32 v[62:63], v[62:63], v[66:67], v[46:47] op_sel_hi:[1,0,1]
	v_mul_f32_e32 v65, 0xbfb8aa3b, v60
	v_exp_f32_e32 v65, v65
	v_pk_fma_f32 v[52:53], v[52:53], v[66:67], v[40:41] op_sel_hi:[1,0,1]
	v_pk_fma_f32 v[54:55], v[54:55], v[66:67], v[42:43] op_sel_hi:[1,0,1]
	v_pk_fma_f32 v[56:57], v[56:57], v[66:67], v[36:37] op_sel_hi:[1,0,1]
	v_add_f32_e32 v65, 1.0, v65
	v_rcp_f32_e32 v68, v65
	v_mul_f32_e32 v65, 0xbfb8aa3b, v61
	v_exp_f32_e32 v65, v65
	v_pk_fma_f32 v[48:49], v[48:49], v[66:67], v[32:33] op_sel_hi:[1,0,1]
	v_pk_fma_f32 v[50:51], v[50:51], v[66:67], v[34:35] op_sel_hi:[1,0,1]
	s_and_b64 vcc, exec, s[6:7]
	v_add_f32_e32 v65, 1.0, v65
	v_rcp_f32_e32 v69, v65
	s_nop 0
	v_pk_mul_f32 v[60:61], v[60:61], v[68:69]
	s_nop 0
	v_pk_mul_f32 v[52:53], v[52:53], v[60:61]
	v_mul_f32_e32 v60, 0xbfb8aa3b, v62
	v_mul_f32_e32 v61, 0xbfb8aa3b, v63
	v_exp_f32_e32 v60, v60
	v_exp_f32_e32 v61, v61
	v_cvt_pk_bf16_f32 v52, v52, v53
	v_add_f32_e32 v60, 1.0, v60
	v_add_f32_e32 v61, 1.0, v61
	v_rcp_f32_e32 v60, v60
	v_rcp_f32_e32 v61, v61
	s_nop 0
	v_pk_mul_f32 v[60:61], v[62:63], v[60:61]
	s_nop 0
	v_pk_mul_f32 v[54:55], v[54:55], v[60:61]
	s_nop 0
	v_cvt_pk_bf16_f32 v53, v54, v55
	v_pk_fma_f32 v[54:55], v[58:59], v[66:67], v[38:39] op_sel_hi:[1,0,1]
	v_mul_f32_e32 v58, 0xbfb8aa3b, v56
	v_mul_f32_e32 v59, 0xbfb8aa3b, v57
	v_exp_f32_e32 v58, v58
	v_exp_f32_e32 v59, v59
	v_add_f32_e32 v58, 1.0, v58
	v_add_f32_e32 v59, 1.0, v59
	v_rcp_f32_e32 v58, v58
	v_rcp_f32_e32 v59, v59
	s_nop 0
	v_pk_mul_f32 v[56:57], v[56:57], v[58:59]
	s_nop 0
	v_pk_mul_f32 v[48:49], v[48:49], v[56:57]
	v_mul_f32_e32 v56, 0xbfb8aa3b, v54
	v_mul_f32_e32 v57, 0xbfb8aa3b, v55
	v_exp_f32_e32 v56, v56
	v_exp_f32_e32 v57, v57
	v_add_f32_e32 v56, 1.0, v56
	v_add_f32_e32 v57, 1.0, v57
	v_rcp_f32_e32 v56, v56
	v_rcp_f32_e32 v57, v57
	s_nop 0
	v_pk_mul_f32 v[54:55], v[54:55], v[56:57]
	s_nop 0
	v_pk_mul_f32 v[50:51], v[50:51], v[54:55]
	v_cvt_pk_bf16_f32 v54, v48, v49
	v_mov_b64_e32 v[48:49], s[12:13]
	v_mad_i64_i32 v[48:49], s[20:21], v64, s1, v[48:49]
	v_lshl_add_u64 v[48:49], s[84:85], 1, v[48:49]
	v_lshl_add_u64 v[48:49], v[48:49], 0, s[52:53]
	v_cvt_pk_bf16_f32 v55, v50, v51
	v_lshl_add_u64 v[48:49], v[48:49], 0, v[128:129]
	s_cbranch_vccnz .LBB0_272
	global_store_dwordx4 v[48:49], v[52:55], off sc0 sc1
	s_cbranch_execnz .LBB0_253

; __device__ __forceinline__ unsigned cvt_pk_bf16(float lo, float hi) { const f32x2 v = {lo, hi}; return __builtin_bit_cast(unsigned, __builtin_convertvector(v, bf16x2_t)); }
; __device__ __forceinline__ float fast_silu(float g) { return g * __builtin_amdgcn_rcpf(1.0f + __builtin_amdgcn_exp2f(-1.4426950408889634f * g)); }
; __device__ __forceinline__ float sum4(f32x4 v) { return (v.x + v.y) + (v.z + v.w); }
; __device__ __forceinline__ float quad_sum(float t, int lane) { t += shx(t, 16, lane); t += shx(t, 32, lane); return t; }
;     template <int A0, int A1> __device__ __forceinline__ void run(const f32x4 (&acc)[2][2][4][2], const Unit& u, int wr, int wc, int fr, int fq) const {
;     ...
;             for (int m = 0; m < 4; ++m) {
;                 const int row = row0 + ai * 128 + m * 16;
;                 const float t = quad_sum(sum4(*(const f32x4*)(ssqp + (size_t)row * 16 + 4 * fq)), fq * 16 + fr);
;                 const float rr = rsqrtf(t * (1.0f / 1024.0f) + EPS);
;                 u32x4 w;
; #pragma unroll
;                 for (int n = 0; n < 2; ++n) {
;                     const f32x4 gg = acc[ai][0][m][n] * rr + bg[n], uu = acc[ai][1][m][n] * rr + bu[n];
;                     const float h0 = fast_silu(gg.x) * uu.x, h1 = fast_silu(gg.y) * uu.y, h2 = fast_silu(gg.z) * uu.z, h3 = fast_silu(gg.w) * uu.w;
;                     w[2 * n] = cvt_pk_bf16(h0, h1); w[2 * n + 1] = cvt_pk_bf16(h2, h3);
;                 }
;                 bf16_t* hp = H + (size_t)row * DFF + u.pn * 128 + wc * 32 + fq * 8;
;                 if (cnt) asm volatile("global_store_dwordx4 %0, %1, off sc0 sc1" :: "v"(hp), "v"(w) : "memory");
;                 else *(u32x4*)hp = w;
.LBB0_253:
	v_add_u32_e32 v48, 0xa0, v160
	v_ashrrev_i32_e32 v49, 31, v48
	v_mov_b64_e32 v[50:51], v[248:249]
	v_mov_b64_e32 v[52:53], v[250:251]
	v_mov_b32_e32 v54, v51
	v_mov_b32_e32 v55, v52
	v_mov_b32_e32 v51, v53
	v_pk_add_f32 v[50:51], v[54:55], v[50:51]
	s_nop 0
	v_add_f32_e32 v49, v50, v51
	v_mov_b32_e32 v50, v49
	s_nop 1
	v_permlane16_swap_b32_e32 v49, v50
	v_add_f32_e32 v49, v49, v50
	v_mov_b32_e32 v50, v49
	s_nop 1
	v_permlane32_swap_b32_e32 v49, v50
	v_add_f32_e32 v49, v49, v50
	v_fmamk_f32 v49, v49, 0x3a800000, v252
	v_cmp_gt_f32_e32 vcc, s49, v49
	v_mul_f32_e32 v50, 0x4b800000, v49
	s_nop 0
	v_cndmask_b32_e32 v49, v49, v50, vcc
	v_rsq_f32_e32 v49, v49
	s_nop 0
	v_mul_f32_e32 v50, 0x45800000, v49
	v_cndmask_b32_e32 v50, v49, v50, vcc
	v_pk_fma_f32 v[28:29], v[28:29], v[50:51], v[44:45] op_sel_hi:[1,0,1]
	v_pk_fma_f32 v[30:31], v[30:31], v[50:51], v[46:47] op_sel_hi:[1,0,1]
	v_mul_f32_e32 v49, 0xbfb8aa3b, v28
	v_exp_f32_e32 v49, v49
	v_pk_fma_f32 v[20:21], v[20:21], v[50:51], v[40:41] op_sel_hi:[1,0,1]
	v_pk_fma_f32 v[22:23], v[22:23], v[50:51], v[42:43] op_sel_hi:[1,0,1]
	v_pk_fma_f32 v[24:25], v[24:25], v[50:51], v[36:37] op_sel_hi:[1,0,1]
	v_add_f32_e32 v49, 1.0, v49
	v_rcp_f32_e32 v52, v49
	v_mul_f32_e32 v49, 0xbfb8aa3b, v29
	v_exp_f32_e32 v49, v49
	v_pk_fma_f32 v[16:17], v[16:17], v[50:51], v[32:33] op_sel_hi:[1,0,1]
	v_pk_fma_f32 v[18:19], v[18:19], v[50:51], v[34:35] op_sel_hi:[1,0,1]
	s_and_b64 vcc, exec, s[6:7]
	v_add_f32_e32 v49, 1.0, v49
	v_rcp_f32_e32 v53, v49
	s_nop 0
	v_pk_mul_f32 v[28:29], v[28:29], v[52:53]
	s_nop 0
	v_pk_mul_f32 v[20:21], v[20:21], v[28:29]
	v_mul_f32_e32 v28, 0xbfb8aa3b, v30
	v_mul_f32_e32 v29, 0xbfb8aa3b, v31
	v_exp_f32_e32 v28, v28
	v_exp_f32_e32 v29, v29
	v_cvt_pk_bf16_f32 v20, v20, v21
	v_add_f32_e32 v28, 1.0, v28
	v_add_f32_e32 v29, 1.0, v29
	v_rcp_f32_e32 v28, v28
	v_rcp_f32_e32 v29, v29
	s_nop 0
	v_pk_mul_f32 v[28:29], v[30:31], v[28:29]
	s_nop 0
	v_pk_mul_f32 v[22:23], v[22:23], v[28:29]
	s_nop 0
	v_cvt_pk_bf16_f32 v21, v22, v23
	v_pk_fma_f32 v[22:23], v[26:27], v[50:51], v[38:39] op_sel_hi:[1,0,1]
	v_mul_f32_e32 v26, 0xbfb8aa3b, v24
	v_mul_f32_e32 v27, 0xbfb8aa3b, v25
	v_exp_f32_e32 v26, v26
	v_exp_f32_e32 v27, v27
	v_add_f32_e32 v26, 1.0, v26
	v_add_f32_e32 v27, 1.0, v27
	v_rcp_f32_e32 v26, v26
	v_rcp_f32_e32 v27, v27
	s_nop 0
	v_pk_mul_f32 v[24:25], v[24:25], v[26:27]
	s_nop 0
	v_pk_mul_f32 v[16:17], v[16:17], v[24:25]
	v_mul_f32_e32 v24, 0xbfb8aa3b, v22
	v_mul_f32_e32 v25, 0xbfb8aa3b, v23
	v_exp_f32_e32 v24, v24
	v_exp_f32_e32 v25, v25
	v_add_f32_e32 v24, 1.0, v24
	v_add_f32_e32 v25, 1.0, v25
	v_rcp_f32_e32 v24, v24
	v_rcp_f32_e32 v25, v25
	s_nop 0
	v_pk_mul_f32 v[22:23], v[22:23], v[24:25]
	s_nop 0
	v_pk_mul_f32 v[18:19], v[18:19], v[22:23]
	v_cvt_pk_bf16_f32 v22, v16, v17
	v_mov_b64_e32 v[16:17], s[12:13]
	v_mad_i64_i32 v[16:17], s[20:21], v48, s1, v[16:17]
	v_lshl_add_u64 v[16:17], s[84:85], 1, v[16:17]
	v_lshl_add_u64 v[16:17], v[16:17], 0, s[52:53]
	v_cvt_pk_bf16_f32 v23, v18, v19
	v_lshl_add_u64 v[16:17], v[16:17], 0, v[128:129]
	s_cbranch_vccnz .LBB0_273
	global_store_dwordx4 v[16:17], v[20:23], off sc0 sc1
	s_cbranch_execnz .LBB0_256

; __device__ __forceinline__ unsigned cvt_pk_bf16(float lo, float hi) { const f32x2 v = {lo, hi}; return __builtin_bit_cast(unsigned, __builtin_convertvector(v, bf16x2_t)); }
; __device__ __forceinline__ float fast_silu(float g) { return g * __builtin_amdgcn_rcpf(1.0f + __builtin_amdgcn_exp2f(-1.4426950408889634f * g)); }
; __device__ __forceinline__ float sum4(f32x4 v) { return (v.x + v.y) + (v.z + v.w); }
; __device__ __forceinline__ float quad_sum(float t, int lane) { t += shx(t, 16, lane); t += shx(t, 32, lane); return t; }
;     template <int A0, int A1> __device__ __forceinline__ void run(const f32x4 (&acc)[2][2][4][2], const Unit& u, int wr, int wc, int fr, int fq) const {
;     ...
;             for (int m = 0; m < 4; ++m) {
;                 const int row = row0 + ai * 128 + m * 16;
;                 const float t = quad_sum(sum4(*(const f32x4*)(ssqp + (size_t)row * 16 + 4 * fq)), fq * 16 + fr);
;                 const float rr = rsqrtf(t * (1.0f / 1024.0f) + EPS);
;                 u32x4 w;
; #pragma unroll
;                 for (int n = 0; n < 2; ++n) {
;                     const f32x4 gg = acc[ai][0][m][n] * rr + bg[n], uu = acc[ai][1][m][n] * rr + bu[n];
;                     const float h0 = fast_silu(gg.x) * uu.x, h1 = fast_silu(gg.y) * uu.y, h2 = fast_silu(gg.z) * uu.z, h3 = fast_silu(gg.w) * uu.w;
;                     w[2 * n] = cvt_pk_bf16(h0, h1); w[2 * n + 1] = cvt_pk_bf16(h2, h3);
;                 }
;                 bf16_t* hp = H + (size_t)row * DFF + u.pn * 128 + wc * 32 + fq * 8;
;                 if (cnt) asm volatile("global_store_dwordx4 %0, %1, off sc0 sc1" :: "v"(hp), "v"(w) : "memory");
;                 else *(u32x4*)hp = w;
;             }
.LBB0_256:
	v_add_u32_e32 v16, 0xb0, v160
	v_ashrrev_i32_e32 v17, 31, v16
	s_waitcnt vmcnt(6)
	v_mov_b64_e32 v[18:19], v[224:225]
	v_mov_b64_e32 v[20:21], v[226:227]
	v_mov_b32_e32 v22, v19
	v_mov_b32_e32 v23, v20
	v_mov_b32_e32 v19, v21
	v_pk_add_f32 v[18:19], v[22:23], v[18:19]
	s_nop 0
	v_add_f32_e32 v17, v18, v19
	v_mov_b32_e32 v18, v17
	s_nop 1
	v_permlane16_swap_b32_e32 v17, v18
	v_add_f32_e32 v17, v17, v18
	v_mov_b32_e32 v18, v17
	s_nop 1
	v_permlane32_swap_b32_e32 v17, v18
	v_add_f32_e32 v17, v17, v18
	v_fmamk_f32 v17, v17, 0x3a800000, v252
	v_cmp_gt_f32_e32 vcc, s49, v17
	v_mul_f32_e32 v18, 0x4b800000, v17
	s_nop 0
	v_cndmask_b32_e32 v17, v17, v18, vcc
	v_rsq_f32_e32 v17, v17
	s_nop 0
	v_mul_f32_e32 v18, 0x45800000, v17
	v_cndmask_b32_e32 v18, v17, v18, vcc
	v_pk_fma_f32 v[12:13], v[12:13], v[18:19], v[44:45] op_sel_hi:[1,0,1]
	v_pk_fma_f32 v[14:15], v[14:15], v[18:19], v[46:47] op_sel_hi:[1,0,1]
	v_mul_f32_e32 v17, 0xbfb8aa3b, v12
	v_exp_f32_e32 v17, v17
	v_pk_fma_f32 v[4:5], v[4:5], v[18:19], v[40:41] op_sel_hi:[1,0,1]
	v_pk_fma_f32 v[6:7], v[6:7], v[18:19], v[42:43] op_sel_hi:[1,0,1]
	v_pk_fma_f32 v[8:9], v[8:9], v[18:19], v[36:37] op_sel_hi:[1,0,1]
	v_add_f32_e32 v17, 1.0, v17
	v_rcp_f32_e32 v20, v17
	v_mul_f32_e32 v17, 0xbfb8aa3b, v13
	v_exp_f32_e32 v17, v17
	v_pk_fma_f32 v[0:1], v[0:1], v[18:19], v[32:33] op_sel_hi:[1,0,1]
	v_pk_fma_f32 v[2:3], v[2:3], v[18:19], v[34:35] op_sel_hi:[1,0,1]
	s_and_b64 vcc, exec, s[6:7]
	v_add_f32_e32 v17, 1.0, v17
	v_rcp_f32_e32 v21, v17
	s_nop 0
	v_pk_mul_f32 v[12:13], v[12:13], v[20:21]
	s_nop 0
	v_pk_mul_f32 v[4:5], v[4:5], v[12:13]
	v_mul_f32_e32 v12, 0xbfb8aa3b, v14
	v_mul_f32_e32 v13, 0xbfb8aa3b, v15
	v_exp_f32_e32 v12, v12
	v_exp_f32_e32 v13, v13
	v_cvt_pk_bf16_f32 v4, v4, v5
	v_add_f32_e32 v12, 1.0, v12
	v_add_f32_e32 v13, 1.0, v13
	v_rcp_f32_e32 v12, v12
	v_rcp_f32_e32 v13, v13
	s_nop 0
	v_pk_mul_f32 v[12:13], v[14:15], v[12:13]
	s_nop 0
	v_pk_mul_f32 v[6:7], v[6:7], v[12:13]
	s_nop 0
	v_cvt_pk_bf16_f32 v5, v6, v7
	v_pk_fma_f32 v[6:7], v[10:11], v[18:19], v[38:39] op_sel_hi:[1,0,1]
	v_mul_f32_e32 v10, 0xbfb8aa3b, v8
	v_mul_f32_e32 v11, 0xbfb8aa3b, v9
	v_exp_f32_e32 v10, v10
	v_exp_f32_e32 v11, v11
	v_add_f32_e32 v10, 1.0, v10
	v_add_f32_e32 v11, 1.0, v11
	v_rcp_f32_e32 v10, v10
	v_rcp_f32_e32 v11, v11
	s_nop 0
	v_pk_mul_f32 v[8:9], v[8:9], v[10:11]
	s_nop 0
	v_pk_mul_f32 v[0:1], v[0:1], v[8:9]
	v_mul_f32_e32 v8, 0xbfb8aa3b, v6
	v_mul_f32_e32 v9, 0xbfb8aa3b, v7
	v_exp_f32_e32 v8, v8
	v_exp_f32_e32 v9, v9
	v_add_f32_e32 v8, 1.0, v8
	v_add_f32_e32 v9, 1.0, v9
	v_rcp_f32_e32 v8, v8
	v_rcp_f32_e32 v9, v9
	s_nop 0
	v_pk_mul_f32 v[6:7], v[6:7], v[8:9]
	s_nop 0
	v_pk_mul_f32 v[2:3], v[2:3], v[6:7]
	v_cvt_pk_bf16_f32 v6, v0, v1
	v_mov_b64_e32 v[0:1], s[12:13]
	v_mad_i64_i32 v[0:1], s[20:21], v16, s1, v[0:1]
	v_lshl_add_u64 v[0:1], s[84:85], 1, v[0:1]
	v_lshl_add_u64 v[0:1], v[0:1], 0, s[52:53]
	v_cvt_pk_bf16_f32 v7, v2, v3
	v_lshl_add_u64 v[0:1], v[0:1], 0, v[128:129]
	s_cbranch_vccnz .LBB0_274
	global_store_dwordx4 v[0:1], v[4:7], off sc0 sc1
	s_cbranch_execnz .LBB0_259
